# prep phase: blocks 0..15 (three rwkv items) hand their fourth work item (a conv item) to blocks 496..511, on top of the G2 tail rebalancing
# baseline (speedup 1.0000x reference)
; __device__ __forceinline__ void phase_prep_scan(const Params& p, int l, bool is_scan, char* smem) {
;   const int G = gridDim.x, bid = blockIdx.x;
;   const int nlong = 256, nshort = 4096;
;   const bool split = (G >= nlong + 64);
;   const bool producer = split && bid >= nlong;
;   unsigned* flags = (unsigned*)(p.ws + OFF_FLAGS) + l * 32;
;   const unsigned wexpect = split ? (unsigned)(G - nlong) : 0u;
;   const int nseg = is_scan ? 4 : (split ? 1 : 3);
;   for (int seg = 0; seg < nseg; ++seg) {
;     int kind, slab = 0, first, limit, stride;
;     if (!is_scan) {
;       kind = 0; slab = seg; first = bid; stride = G; limit = (seg == 0) ? (1040 + 688 + 16) : 688;
;     } else if (seg == 0 || seg == 2) {
;       kind = 0; slab = (seg == 0) ? 1 : 2; limit = 688;
;       if (producer) { first = bid - nlong; stride = G - nlong; } else { first = limit; stride = 1; }
;     } else if (seg == 1) {
;       kind = 1;
;       if (split) {
;         if (bid < nlong) { first = bid; stride = G; limit = nlong; }
;         else { first = bid; stride = G - nlong; limit = nlong + nshort; }
;       } else { first = bid; stride = G; limit = nlong + nshort; }
;     } else {
;       kind = 2;
;       const int n_conv = (NPAD / 64) * 16;
;       limit = (l + 1 < DEPTH) ? n_conv : 0;
;       if (split) { first = producer ? bid - nlong : limit; stride = producer ? G - nlong : 1; }
;       else { first = bid; stride = G; }
;       __syncthreads();
;     }
;     for (int i = first; i < limit; i += stride) {
;       if (kind == 0) {
;         prep_item(p, l, is_scan || seg > 0, slab, i, smem);
.LBB0_51:
	s_add_i32 s22, s22, s84
	s_cmpk_lg_i32 s15, 0x6d0
	s_cbranch_scc1 .Lprb_std
	s_cmpk_lg_i32 s84, 0x200
	s_cbranch_scc1 .Lprb_std
	s_sub_i32 s0, s22, 0x600
	s_cmp_lt_u32 s0, 16
	s_cbranch_scc0 .Lprb_hi
	v_readlane_b32 s1, v244, 0
	s_cmp_lt_u32 s1, 16
	s_cbranch_scc1 .LBB0_699
	s_branch .Lprb_std
.Lprb_hi:
	s_sub_i32 s0, s22, 0x7f0
	s_cmp_lt_u32 s0, 16
	s_cbranch_scc0 .Lprb_std
	s_add_i32 s22, s0, 0x600
.Lprb_std:
	s_cmp_ge_i32 s22, s15
	s_cbranch_scc1 .LBB0_699
.LBB0_52:
	s_mov_b64 s[16:17], -1
	s_and_b64 vcc, exec, s[64:65]
	s_cbranch_vccz .LBB0_314
	v_readlane_b32 s0, v240, 46
	v_readlane_b32 s1, v240, 47
	s_and_b64 vcc, exec, s[0:1]
	s_cbranch_vccz .LBB0_117
	s_lshl_b32 s14, s22, 2
	v_mov_b32_e32 v4, v178
	s_movk_i32 s16, 0x10ff
	v_bfi_b32 v0, 63, v4, s14
	v_cmp_lt_i32_e32 vcc, s16, v0
	s_and_saveexec_b64 s[16:17], vcc
	s_xor_b64 s[16:17], exec, s[16:17]
	s_cbranch_execz .LBB0_68
	s_cmpk_gt_u32 s14, 0x12ff
	s_mov_b64 s[38:39], -1
	s_cbranch_scc0 .LBB0_65
	s_cmpk_gt_u32 s14, 0x14ff
	s_cbranch_scc0 .LBB0_62
	s_cmpk_gt_u32 s14, 0x16ff
	s_cbranch_scc0 .LBB0_59
	v_add_u32_e32 v2, 0xffffff90, v0
	s_mov_b64 s[38:39], 0
